# v019 plus indexer wave 4-7 stagger s_sleep 11 per step
# baseline (speedup 1.0000x reference)
; #define LAS __attribute__((address_space(3)))
; __device__ __forceinline__ void indexer_phase_wg(const bf16_t* qkv, const float* wi32, float* scores, LAS unsigned char* lds, int bid, int G, int tid, int wave, int lane) {
;     ...
;         for (int st = 0; st < nstep; ++st) {
;             if (st + 1 < nstep) { const int r0 = 128 * (st + 1);
;                 kreg0 = *(const u32x4*)(kg + (size_t)min(r0, lastrow - srow) * LDQ); kreg1 = *(const u32x4*)(kg + (size_t)min(r0 + 64, lastrow - srow) * LDQ); }
;             const LAS unsigned char* buf = lds + (st & 1) * 16384;
; #pragma unroll
;             for (int sub = 0; sub < 4; ++sub) {
;                 const int k0 = 128 * st + 32 * sub;
;                 {
;                     const int key = k0 + r32, lrow = 32 * (sub & 1) + r32;
;                     const LAS unsigned char* img = buf + (sub >> 1) * 8192;
;                     bf16x8 kf[4];
; #pragma unroll
;                     for (int ks = 0; ks < 4; ++ks) kf[ks] = *(const LAS bf16x8*)(img + lrow * 128 + (((2 * ks + hi) ^ ((lrow >> 1) & 7)) * 16));
.LBB0_442:
	v_readlane_b32 s98, v250, 4
	s_cmp_lt_u32 s98, 4
	s_cbranch_scc1 .Lidx_nostag
	s_sleep 11
